# D1->D2->A as closed chains of 4 workgroups per (batch, 128-token tile): D2 rows remapped to the tile the same workgroups produced/consume; the two group barriers around D2 become a 4-workgroup arrival
# speedup vs baseline: 1.0662x; 1.0112x over previous
; DI unsigned xb_ld(unsigned* p)              { return __hip_atomic_load(p, __ATOMIC_RELAXED, __HIP_MEMORY_SCOPE_AGENT); }
; DI unsigned xb_add(unsigned* p, unsigned v) { return __hip_atomic_fetch_add(p, v, __ATOMIC_RELAXED, __HIP_MEMORY_SCOPE_AGENT); }
; #define XB_SPIN(cond, bar) do { unsigned _sp = 0; while (cond) { __builtin_amdgcn_s_sleep(1); \
;     if ((++_sp & 255u) == 0u) { if (xb_ld(&(bar)[XB_TMO])) break; if (_sp > XB_SPIN_CAP) { atomicAdd(&(bar)[XB_TMO], 1u); break; } } } } while (0)
; DI void xcd_barrier(const XcdBarrier& b) {
;     asm volatile("s_waitcnt vmcnt(0)" ::: "memory");
;     __syncthreads();
;     if (threadIdx.x == 0) {
;         unsigned* bar = b.bar;
;         __builtin_amdgcn_s_waitcnt(0);
;         unsigned nloc = b.st[0], nx = b.st[1];
;         if (nloc == 0u) { xcd_barrier_complete(bar, b.x, b.G, nloc, nx); b.st[0] = nloc; b.st[1] = nx; }
;         const unsigned old = xb_add(&bar[XB_XSUB(b.x)], 1u);
;         const unsigned gen = old / nloc;
;         if (old + 1u == (gen + 1u) * nloc) {
;             if (nx > 1u) {
;               __builtin_amdgcn_fence(__ATOMIC_RELEASE, "agent");
;               asm volatile("s_waitcnt vmcnt(0)" ::: "memory");
;               const unsigned og = xb_add(&bar[XB_TOP], 1u);
;               const unsigned tg = og / nx;
;               if (og + 1u == (tg + 1u) * nx) xb_add(&bar[XB_TOPGEN], 1u);
;               else XB_SPIN(xb_ld(&bar[XB_TOPGEN]) == tg, bar);
;             }
;             __builtin_amdgcn_fence(__ATOMIC_ACQUIRE, "agent");
;             xb_add(&bar[XB_XGEN(b.x)], 1u);
;             asm volatile("s_waitcnt vmcnt(0)" ::: "memory");
;         } else {
;             XB_SPIN(xb_ld(&bar[XB_XGEN(b.x)]) == gen, bar);
;             __builtin_amdgcn_fence(__ATOMIC_ACQUIRE, "agent");
;             asm volatile("s_waitcnt vmcnt(0)" ::: "memory");
;         }
;     }
;     __syncthreads();
; }
; __global__ void __launch_bounds__(256, 2) hybrid_megakernel(Params p) {
;     ...
;     xcd_barrier(xg);
;     for (int it = bid; it < 512; it += nb) outproj_item(p, l, it, lds);
;     xcd_barrier(xg);
.Lxg_t0_4:
	v_readlane_b32 s6, v235, 22
	s_waitcnt vmcnt(0) lgkmcnt(0)
	s_nop 0
	v_mov_b32_e32 v0, s6
	ds_read_b32 v0, v0 offset:4
	s_waitcnt lgkmcnt(0)
	v_cmp_eq_u32_e32 vcc, 1, v0
	s_cbranch_vccz .Lq_orig_4
	v_readlane_b32 s6, v235, 0
	v_readlane_b32 s8, v234, 24
	s_and_b32 s7, s6, 7
	s_add_u32 s7, s7, 1
	s_lshl_b32 s7, s7, 14
	s_bfe_u32 s9, s6, 0x40003
	s_lshl_b32 s9, s9, 7
	s_add_u32 s7, s7, s9
	s_add_u32 s7, s7, 0xf4f3600
	s_add_u32 s4, s90, s7
	s_addc_u32 s5, s91, 0
	s_lshl_b32 s8, s8, 3
	s_add_u32 s8, s8, 4
	global_atomic_add v179, v188, s[4:5]
	s_mov_b32 s16, 0
.Lq_poll_4:
	global_load_dword v1, v179, s[4:5] sc1
	s_waitcnt vmcnt(0)
	v_cmp_le_u32_e32 vcc, s8, v1
	s_cbranch_vccnz .Lq_done_4
	s_sleep 1
	s_add_i32 s16, s16, 1
	s_cmp_lt_u32 s16, 0x8000
	s_cbranch_scc1 .Lq_poll_4
.Lq_done_4:
	s_branch .LBB0_587
.Lq_orig_4:
	v_readlane_b32 s2, v235, 22
	s_waitcnt vmcnt(0) expcnt(0) lgkmcnt(0)
	s_nop 0
	v_mov_b32_e32 v0, s2
	ds_read_b32 v2, v0
	ds_read_b32 v1, v0 offset:4
	s_waitcnt lgkmcnt(1)
	v_cmp_ne_u32_e32 vcc, 0, v2
	s_cbranch_vccnz .LBB0_556
	s_mov_b32 s8, 1
	s_branch .LBB0_546

; __global__ void __launch_bounds__(256, 2) hybrid_megakernel(Params p) {
;     ...
;     const float* xin = (l == 0) ? p.x : p.out;
;     for (int vb = bid; vb < 512; vb += nb)
;       for (int j = vb >> 3; j < 128; j += 64) resid_rows<4>(p, l, (vb & 7) * 2048 + j * 16 + wid * 4, xin);
.LBB0_590:
	s_bfe_u32 s7, s13, 0x40003
	s_lshl_b32 s7, s7, 7
	s_lshr_b32 s14, s13, 7
	s_lshl_b32 s14, s14, 5
	s_add_i32 s7, s7, s14
	s_and_b32 s6, s12, 0x3800
	s_add_i32 s7, s7, s6
	s_movk_i32 s14, 0xffc0
	v_add_u32_e32 v104, s7, v177
	s_branch .LBB0_592
.LBB0_591:
	s_or_b64 exec, exec, s[6:7]
	s_add_i32 s14, s14, 64
	s_cmp_gt_i32 s14, 63
	v_add_u32_e32 v104, 16, v104
	s_cbranch_scc1 .LBB0_589

; DI unsigned xb_ld(unsigned* p)              { return __hip_atomic_load(p, __ATOMIC_RELAXED, __HIP_MEMORY_SCOPE_AGENT); }
; DI unsigned xb_add(unsigned* p, unsigned v) { return __hip_atomic_fetch_add(p, v, __ATOMIC_RELAXED, __HIP_MEMORY_SCOPE_AGENT); }
; #define XB_SPIN(cond, bar) do { unsigned _sp = 0; while (cond) { __builtin_amdgcn_s_sleep(1); \
;     if ((++_sp & 255u) == 0u) { if (xb_ld(&(bar)[XB_TMO])) break; if (_sp > XB_SPIN_CAP) { atomicAdd(&(bar)[XB_TMO], 1u); break; } } } } while (0)
; DI void xcd_barrier(const XcdBarrier& b) {
;     asm volatile("s_waitcnt vmcnt(0)" ::: "memory");
;     __syncthreads();
;     if (threadIdx.x == 0) {
;         unsigned* bar = b.bar;
;         __builtin_amdgcn_s_waitcnt(0);
;         unsigned nloc = b.st[0], nx = b.st[1];
;         if (nloc == 0u) { xcd_barrier_complete(bar, b.x, b.G, nloc, nx); b.st[0] = nloc; b.st[1] = nx; }
;         const unsigned old = xb_add(&bar[XB_XSUB(b.x)], 1u);
;         const unsigned gen = old / nloc;
;         if (old + 1u == (gen + 1u) * nloc) {
;             if (nx > 1u) {
;               __builtin_amdgcn_fence(__ATOMIC_RELEASE, "agent");
;               asm volatile("s_waitcnt vmcnt(0)" ::: "memory");
;               const unsigned og = xb_add(&bar[XB_TOP], 1u);
;               const unsigned tg = og / nx;
;               if (og + 1u == (tg + 1u) * nx) xb_add(&bar[XB_TOPGEN], 1u);
;               else XB_SPIN(xb_ld(&bar[XB_TOPGEN]) == tg, bar);
;             }
;             __builtin_amdgcn_fence(__ATOMIC_ACQUIRE, "agent");
;             xb_add(&bar[XB_XGEN(b.x)], 1u);
;             asm volatile("s_waitcnt vmcnt(0)" ::: "memory");
;         } else {
;             XB_SPIN(xb_ld(&bar[XB_XGEN(b.x)]) == gen, bar);
;             __builtin_amdgcn_fence(__ATOMIC_ACQUIRE, "agent");
;             asm volatile("s_waitcnt vmcnt(0)" ::: "memory");
;         }
;     }
;     __syncthreads();
; }
; __global__ void __launch_bounds__(256, 2) hybrid_megakernel(Params p) {
;     ...
;     for (int vb = bid; vb < 512; vb += nb)
;       for (int j = vb >> 3; j < 128; j += 64) resid_rows<4>(p, l, (vb & 7) * 2048 + j * 16 + wid * 4, xin);
;     if (l < 3) xcd_barrier(xg);
.Lxg_t0_5:
	v_readlane_b32 s6, v235, 22
	s_waitcnt vmcnt(0) lgkmcnt(0)
	s_nop 0
	v_mov_b32_e32 v0, s6
	ds_read_b32 v0, v0 offset:4
	s_waitcnt lgkmcnt(0)
	v_cmp_eq_u32_e32 vcc, 1, v0
	s_cbranch_vccz .Lq_orig_5
	v_readlane_b32 s6, v235, 0
	v_readlane_b32 s8, v234, 24
	s_and_b32 s7, s6, 7
	s_add_u32 s7, s7, 1
	s_lshl_b32 s7, s7, 14
	s_bfe_u32 s9, s6, 0x40003
	s_lshl_b32 s9, s9, 7
	s_add_u32 s7, s7, s9
	s_add_u32 s7, s7, 0xf4f3600
	s_add_u32 s4, s90, s7
	s_addc_u32 s5, s91, 0
	s_lshl_b32 s8, s8, 3
	s_add_u32 s8, s8, 8
	global_atomic_add v179, v188, s[4:5]
	s_mov_b32 s16, 0

; DI unsigned xb_ld(unsigned* p)              { return __hip_atomic_load(p, __ATOMIC_RELAXED, __HIP_MEMORY_SCOPE_AGENT); }
; DI unsigned xb_add(unsigned* p, unsigned v) { return __hip_atomic_fetch_add(p, v, __ATOMIC_RELAXED, __HIP_MEMORY_SCOPE_AGENT); }
; #define XB_SPIN(cond, bar) do { unsigned _sp = 0; while (cond) { __builtin_amdgcn_s_sleep(1); \
;     if ((++_sp & 255u) == 0u) { if (xb_ld(&(bar)[XB_TMO])) break; if (_sp > XB_SPIN_CAP) { atomicAdd(&(bar)[XB_TMO], 1u); break; } } } } while (0)
; DI void xcd_barrier(const XcdBarrier& b) {
;     asm volatile("s_waitcnt vmcnt(0)" ::: "memory");
;     __syncthreads();
;     if (threadIdx.x == 0) {
;         unsigned* bar = b.bar;
;         __builtin_amdgcn_s_waitcnt(0);
;         unsigned nloc = b.st[0], nx = b.st[1];
;         if (nloc == 0u) { xcd_barrier_complete(bar, b.x, b.G, nloc, nx); b.st[0] = nloc; b.st[1] = nx; }
;         const unsigned old = xb_add(&bar[XB_XSUB(b.x)], 1u);
;         const unsigned gen = old / nloc;
;         if (old + 1u == (gen + 1u) * nloc) {
;             if (nx > 1u) {
;               __builtin_amdgcn_fence(__ATOMIC_RELEASE, "agent");
;               asm volatile("s_waitcnt vmcnt(0)" ::: "memory");
;               const unsigned og = xb_add(&bar[XB_TOP], 1u);
;               const unsigned tg = og / nx;
;               if (og + 1u == (tg + 1u) * nx) xb_add(&bar[XB_TOPGEN], 1u);
;               else XB_SPIN(xb_ld(&bar[XB_TOPGEN]) == tg, bar);
;             }
;             __builtin_amdgcn_fence(__ATOMIC_ACQUIRE, "agent");
;             xb_add(&bar[XB_XGEN(b.x)], 1u);
;             asm volatile("s_waitcnt vmcnt(0)" ::: "memory");
;         } else {
;             XB_SPIN(xb_ld(&bar[XB_XGEN(b.x)]) == gen, bar);
;             __builtin_amdgcn_fence(__ATOMIC_ACQUIRE, "agent");
;             asm volatile("s_waitcnt vmcnt(0)" ::: "memory");
;         }
;     }
;     __syncthreads();
; }
; __global__ void __launch_bounds__(256, 2) hybrid_megakernel(Params p) {
;     ...
;     for (int vb = bid; vb < 512; vb += nb)
;       for (int j = vb >> 3; j < 128; j += 64) resid_rows<4>(p, l, (vb & 7) * 2048 + j * 16 + wid * 4, xin);
;     if (l < 3) xcd_barrier(xg);
.Lq_done_5:
	s_branch .LBB0_159
.Lq_orig_5:
	v_readlane_b32 s2, v235, 22
	s_waitcnt vmcnt(0) expcnt(0) lgkmcnt(0)
	s_nop 0
	v_mov_b32_e32 v0, s2
	ds_read_b32 v2, v0
	ds_read_b32 v1, v0 offset:4
	s_waitcnt lgkmcnt(1)
	v_cmp_ne_u32_e32 vcc, 0, v2
	s_cbranch_vccnz .LBB0_647
	s_mov_b32 s8, 1
	s_branch .LBB0_637
